# Hyena spectrum-multiply loop: the four filter-spectrum loads of both unrolled halves issued up front (counted vmcnt) instead of load-wait pairs
# baseline (speedup 1.0000x reference)
.LBB0_394:
	v_mov_b32_e32 v86, v138
	v_lshl_add_u64 v[150:151], v[86:87], 3, s[78:79]
	v_mov_b32_e32 v86, v139
	v_lshl_add_u64 v[156:157], v[86:87], 3, s[78:79]
	global_load_dwordx2 v[246:247], v[150:151], off
	global_load_dwordx2 v[248:249], v[156:157], off
	v_add_u32_e32 v86, 0x400, v138
	v_lshl_add_u64 v[150:151], v[86:87], 3, s[78:79]
	v_add_u32_e32 v86, 0x400, v139
	v_lshl_add_u64 v[156:157], v[86:87], 3, s[78:79]
	global_load_dwordx2 v[250:251], v[150:151], off
	global_load_dwordx2 v[252:253], v[156:157], off
	v_add_u32_e32 v138, 0x800, v138
	v_add_u32_e32 v139, 0x800, v139
	ds_read2st64_b64 v[150:153], v140 offset1:8
	s_add_i32 s52, s52, 4
	v_cmp_eq_u32_e32 vcc, s52, v191
	s_or_b64 s[0:1], vcc, s[0:1]
	s_waitcnt lgkmcnt(0)
	v_mov_b32_e32 v154, v150
	v_mov_b32_e32 v155, v152
	v_mov_b32_e32 v152, v151
	s_waitcnt vmcnt(2)
	v_mov_b32_e32 v204, v246
	v_mov_b32_e32 v205, v248
	v_mov_b32_e32 v156, v247
	v_mov_b32_e32 v157, v249
	v_pk_mul_f32 v[150:151], v[152:153], v[156:157]
	s_nop 0
	v_pk_fma_f32 v[150:151], v[154:155], v[204:205], v[150:151] neg_lo:[0,0,1] neg_hi:[0,0,1]
	v_pk_mul_f32 v[154:155], v[154:155], v[156:157]
	s_nop 0
	v_pk_fma_f32 v[152:153], v[152:153], v[204:205], v[154:155]
	v_mov_b32_e32 v154, v150
	s_nop 0
	v_mov_b32_e32 v155, v152
	v_mov_b32_e32 v152, v151
	ds_write2st64_b64 v140, v[154:155], v[152:153] offset1:8
	ds_read2st64_b64 v[150:153], v140 offset0:16 offset1:24
	s_waitcnt lgkmcnt(0)
	v_mov_b32_e32 v156, v150
	v_mov_b32_e32 v157, v152
	v_mov_b32_e32 v152, v151
	s_waitcnt vmcnt(0)
	v_mov_b32_e32 v204, v250
	v_mov_b32_e32 v205, v252
	v_mov_b32_e32 v154, v251
	v_mov_b32_e32 v155, v253
	v_pk_mul_f32 v[150:151], v[152:153], v[154:155]
	v_pk_mul_f32 v[154:155], v[156:157], v[154:155]
	v_pk_fma_f32 v[150:151], v[156:157], v[204:205], v[150:151] neg_lo:[0,0,1] neg_hi:[0,0,1]
	v_pk_fma_f32 v[152:153], v[152:153], v[204:205], v[154:155]
	v_mov_b32_e32 v154, v150
	s_nop 0
	v_mov_b32_e32 v155, v152
	v_mov_b32_e32 v152, v151
	ds_write2st64_b64 v140, v[154:155], v[152:153] offset0:16 offset1:24
	v_add_u32_e32 v140, 0x4000, v140
	s_andn2_b64 exec, exec, s[0:1]
	s_cbranch_execnz .LBB0_394
	s_or_b64 exec, exec, s[0:1]
	s_and_saveexec_b64 s[0:1], s[18:19]
	s_cbranch_execz .LBB0_397
	v_mov_b32_e32 v86, v138
	v_lshl_add_u64 v[140:141], v[86:87], 3, s[78:79]
	v_mov_b32_e32 v86, v139
	v_lshl_add_u64 v[138:139], v[86:87], 3, s[78:79]
	global_load_dwordx2 v[150:151], v[140:141], off
	global_load_dwordx2 v[152:153], v[138:139], off
	v_lshlrev_b32_e32 v86, 3, v164
	v_lshl_or_b32 v86, v191, 12, v86
	v_add_u32_e32 v86, 0, v86
	ds_read2st64_b64 v[138:141], v86 offset1:8
	s_waitcnt lgkmcnt(0)
	v_mov_b32_e32 v154, v138
	v_mov_b32_e32 v155, v140
	v_mov_b32_e32 v140, v139
	s_waitcnt vmcnt(1)
	v_mov_b32_e32 v138, v150
	s_waitcnt vmcnt(0)
	v_mov_b32_e32 v139, v152
	v_mov_b32_e32 v152, v151
	v_pk_mul_f32 v[150:151], v[140:141], v[152:153]
	v_pk_mul_f32 v[152:153], v[154:155], v[152:153]
	v_pk_fma_f32 v[150:151], v[154:155], v[138:139], v[150:151] neg_lo:[0,0,1] neg_hi:[0,0,1]
	v_pk_fma_f32 v[138:139], v[140:141], v[138:139], v[152:153]
	v_mov_b32_e32 v140, v150
	v_mov_b32_e32 v141, v138
	v_mov_b32_e32 v138, v151
	ds_write2st64_b64 v86, v[140:141], v[138:139] offset1:8
